# post0: rotary-table vectors of both rows requested at the top of each iteration
# baseline (speedup 1.0000x reference)
.LBB0_35:
	s_mov_b32 s44, 0
	s_add_i32 s2, s44, s76
	s_waitcnt vmcnt(0)
	v_mbcnt_lo_u32_b32 v0, -1, 0
	v_mbcnt_hi_u32_b32 v0, -1, v0
	s_add_i32 s18, s44, s69
	v_lshl_add_u32 v176, s2, 6, v0
	s_add_i32 s82, s44, s72
	v_readfirstlane_b32 s2, v176
	s_ashr_i32 s6, s2, 6
	v_readlane_b32 s4, v254, 11
	s_cmp_gt_u32 s4, 16
	s_cselect_b64 s[2:3], -1, 0
	s_cmp_lt_u32 s4, 17
	s_cselect_b64 s[10:11], -1, 0
	s_and_b64 s[4:5], s[10:11], exec
	s_mov_b32 s4, 0x12000
	s_cselect_b32 s4, s4, 0x10000
	s_lshl_b32 s5, s82, 3
	s_abs_i32 s7, s5
	v_cvt_f32_u32_e32 v1, s7
	s_mov_b32 s14, s18
	v_writelane_b32 v254, s14, 41
	s_lshl_b32 s13, s18, 3
	v_rcp_iflag_f32_e32 v1, v1
	v_writelane_b32 v254, s15, 42
	s_add_i32 s6, s6, s13
	s_sub_i32 s13, 0, s7
	v_mul_f32_e32 v1, 0x4f7ffffe, v1
	v_cvt_u32_f32_e32 v1, v1
	s_add_i32 s12, s4, s5
	s_add_i32 s12, s12, -1
	s_xor_b32 s5, s12, s5
	v_readfirstlane_b32 s14, v1
	s_mul_i32 s13, s13, s14
	s_mul_hi_u32 s13, s14, s13
	s_abs_i32 s12, s12
	s_add_i32 s14, s14, s13
	s_mul_hi_u32 s13, s12, s14
	s_mul_i32 s14, s13, s7
	s_sub_i32 s12, s12, s14
	s_ashr_i32 s5, s5, 31
	s_add_i32 s14, s13, 1
	s_sub_i32 s15, s12, s7
	s_cmp_ge_u32 s12, s7
	s_cselect_b32 s13, s14, s13
	s_cselect_b32 s12, s15, s12
	s_add_i32 s14, s13, 1
	s_cmp_ge_u32 s12, s7
	s_cselect_b32 s7, s14, s13
	s_xor_b32 s7, s7, s5
	s_sub_i32 s5, s7, s5
	s_mul_i32 s56, s5, s6
	s_add_i32 s5, s56, s5
	s_min_i32 s57, s5, s4
	s_cmp_ge_i32 s56, s57
	s_mov_b32 s54, 0x800000
	s_cbranch_scc1 .LBB0_134
	v_readlane_b32 s28, v254, 11
	s_cmp_lg_u32 s28, 21
	s_cselect_b64 s[6:7], -1, 0
	s_cmp_eq_u32 s28, 21
	s_cselect_b64 s[12:13], -1, 0
	s_cmp_eq_u32 s28, 17
	s_cselect_b64 s[14:15], -1, 0
	s_lshl_b64 s[4:5], s[44:45], 3
	s_add_u32 s22, s70, s4
	v_readlane_b32 s24, v253, 62
	s_addc_u32 s23, s71, s5
	v_readlane_b32 s26, v254, 0
	v_readlane_b32 s27, v254, 1
	s_add_u32 s4, s26, s44
	s_addc_u32 s5, s27, 0
	s_lshl_b64 s[18:19], s[44:45], 2
	v_readlane_b32 s25, v253, 63
	s_add_u32 s58, s24, s18
	s_addc_u32 s59, s25, s19
	s_cmp_eq_u32 s28, 10
	s_cselect_b64 s[18:19], -1, 0
	s_and_b64 s[20:21], s[18:19], exec
	s_movk_i32 s20, 0x400
	s_cselect_b32 s60, s20, 0x1000
	s_cselect_b32 s61, 0, 0xc00
	s_or_b64 s[12:13], s[18:19], s[12:13]
	s_and_b64 s[18:19], s[12:13], exec
	s_cselect_b32 s18, 64, 48
	s_add_u32 s18, s22, s18
	s_addc_u32 s19, s23, 0
	s_load_dwordx2 s[18:19], s[18:19], 0x0
	s_and_b64 s[10:11], s[10:11], exec
	s_cselect_b32 s20, 0, 0x1000
	v_and_b32_e32 v34, 63, v0
	v_lshlrev_b32_e32 v192, 5, v34
	s_waitcnt lgkmcnt(0)
	s_add_u32 s10, s18, s20
	s_addc_u32 s11, s19, 0
	s_and_b64 s[12:13], s[12:13], exec
	s_cselect_b32 s12, 0x48, 56
	s_add_u32 s12, s22, s12
	s_addc_u32 s13, s23, 0
	s_load_dwordx2 s[12:13], s[12:13], 0x0
	v_xor_b32_e32 v32, 1, v229
	v_cmp_lt_i32_e32 vcc, v32, v231
	v_mov_b32_e32 v33, v193
	v_mov_b32_e32 v62, 0
	s_waitcnt lgkmcnt(0)
	s_add_u32 s12, s12, s20
	s_addc_u32 s13, s13, 0
	global_load_dwordx4 v[0:3], v192, s[10:11] offset:16
	global_load_dwordx4 v[4:7], v192, s[10:11]
	global_load_dwordx4 v[8:11], v192, s[12:13] offset:16
	global_load_dwordx4 v[12:15], v192, s[12:13]
	global_load_dwordx4 v[16:19], v192, s[10:11] offset:2064
	global_load_dwordx4 v[20:23], v192, s[10:11] offset:2048
	global_load_dwordx4 v[24:27], v192, s[12:13] offset:2064
	global_load_dwordx4 v[28:31], v192, s[12:13] offset:2048
	v_cndmask_b32_e32 v32, v229, v32, vcc
	v_lshlrev_b32_e32 v109, 2, v32
	v_xor_b32_e32 v32, 2, v229
	v_cmp_lt_i32_e32 vcc, v32, v231
	s_cmp_eq_u32 s28, 6
	s_cselect_b64 s[10:11], -1, 0
	v_cndmask_b32_e32 v32, v229, v32, vcc
	v_lshlrev_b32_e32 v121, 2, v32
	v_xor_b32_e32 v32, 4, v229
	v_cmp_lt_i32_e32 vcc, v32, v231
	s_and_b64 s[12:13], s[10:11], exec
	s_mov_b32 s12, 0x44d4000
	v_cndmask_b32_e32 v32, v229, v32, vcc
	v_lshlrev_b32_e32 v122, 2, v32
	v_xor_b32_e32 v32, 8, v229
	v_cmp_lt_i32_e32 vcc, v32, v231
	s_cselect_b32 s12, s12, 0x459a000
	s_or_b64 s[10:11], s[10:11], s[14:15]
	v_cndmask_b32_e32 v32, v229, v32, vcc
	v_lshlrev_b32_e32 v123, 2, v32
	v_xor_b32_e32 v32, 16, v229
	v_cmp_lt_i32_e32 vcc, v32, v231
	s_add_u32 s62, s4, 0x38260000
	s_addc_u32 s63, s5, 0
	v_cndmask_b32_e32 v32, v229, v32, vcc
	v_lshlrev_b32_e32 v124, 2, v32
	v_xor_b32_e32 v32, 32, v229
	s_add_u32 s64, s4, 0x3d2e4000
	v_cmp_lt_i32_e32 vcc, v32, v231
	s_addc_u32 s65, s5, 0
	s_add_u32 s14, s4, s12
	v_cndmask_b32_e32 v32, v229, v32, vcc
	v_lshlrev_b32_e32 v125, 2, v32
	v_lshlrev_b32_e32 v32, 4, v34
	s_addc_u32 s15, s5, 0
	v_lshl_add_u64 v[32:33], s[4:5], 0, v[32:33]
	s_mov_b64 s[4:5], 0x4660000
	v_lshl_add_u64 v[110:111], v[32:33], 0, s[4:5]
	v_cmp_eq_u32_e32 vcc, 0, v34
	s_mov_b64 s[4:5], 0x16660000
	v_lshlrev_b32_e32 v108, 3, v34
	s_mov_b32 s68, -1
	s_and_b64 s[12:13], s[6:7], vcc
	v_lshl_add_u64 v[112:113], s[14:15], 0, v[192:193]
	v_lshl_add_u64 v[114:115], v[32:33], 0, s[4:5]
	v_mov_b32_e32 v63, v62
	v_mov_b32_e32 v54, v62
	v_mov_b32_e32 v55, v62
	v_mov_b32_e32 v60, v62
	v_mov_b32_e32 v61, v62
	v_mov_b32_e32 v52, v62
	v_mov_b32_e32 v53, v62
	v_mov_b32_e32 v58, v62
	v_mov_b32_e32 v59, v62
	v_mov_b32_e32 v50, v62
	v_mov_b32_e32 v51, v62
	v_mov_b32_e32 v56, v62
	v_mov_b32_e32 v57, v62
	v_mov_b32_e32 v48, v62
	v_mov_b32_e32 v49, v62
	v_mov_b32_e32 v38, v62
	v_mov_b32_e32 v39, v62
	v_mov_b32_e32 v46, v62
	v_mov_b32_e32 v47, v62
	v_mov_b32_e32 v36, v62
	v_mov_b32_e32 v37, v62
	v_mov_b32_e32 v44, v62
	v_mov_b32_e32 v45, v62
	v_mov_b32_e32 v34, v62
	v_mov_b32_e32 v35, v62
	v_mov_b32_e32 v42, v62
	v_mov_b32_e32 v43, v62
	v_mov_b32_e32 v32, v62
	v_mov_b32_e32 v33, v62
	v_mov_b32_e32 v40, v62
	v_mov_b32_e32 v41, v62
	s_add_i32 s98, s56, 0
	s_ashr_i32 s99, s98, 11
	s_mulk_i32 s99, 0x900
	s_and_b32 s100, s98, 0x7ff
	s_add_i32 s99, s99, s100
	s_addk_i32 s99, 0x100
	s_and_b64 s[100:101], s[2:3], exec
	s_cselect_b32 s98, s99, s98
	s_ashr_i32 s99, s98, 31
	s_lshl_b64 s[98:99], s[98:99], 11
	v_lshl_add_u64 v[168:169], v[110:111], 0, s[98:99]
	global_load_dwordx4 v[136:139], v[168:169], off
	global_load_dwordx4 v[140:143], v[168:169], off offset:1024
	s_add_i32 s98, s56, 1
	s_ashr_i32 s99, s98, 11
	s_mulk_i32 s99, 0x900
	s_and_b32 s100, s98, 0x7ff
	s_add_i32 s99, s99, s100
	s_addk_i32 s99, 0x100
	s_and_b64 s[100:101], s[2:3], exec
	s_cselect_b32 s98, s99, s98
	s_ashr_i32 s99, s98, 31
	s_lshl_b64 s[98:99], s[98:99], 11
	v_lshl_add_u64 v[170:171], v[110:111], 0, s[98:99]
	global_load_dwordx4 v[144:147], v[170:171], off
	global_load_dwordx4 v[148:151], v[170:171], off offset:1024
	s_add_i32 s98, s56, 2
	s_ashr_i32 s99, s98, 11
	s_mulk_i32 s99, 0x900
	s_and_b32 s100, s98, 0x7ff
	s_add_i32 s99, s99, s100
	s_addk_i32 s99, 0x100
	s_and_b64 s[100:101], s[2:3], exec
	s_cselect_b32 s98, s99, s98
	s_ashr_i32 s99, s98, 31
	s_lshl_b64 s[98:99], s[98:99], 11
	v_lshl_add_u64 v[172:173], v[110:111], 0, s[98:99]
	global_load_dwordx4 v[152:155], v[172:173], off
	global_load_dwordx4 v[156:159], v[172:173], off offset:1024
	s_add_i32 s98, s56, 3
	s_ashr_i32 s99, s98, 11
	s_mulk_i32 s99, 0x900
	s_and_b32 s100, s98, 0x7ff
	s_add_i32 s99, s99, s100
	s_addk_i32 s99, 0x100
	s_and_b64 s[100:101], s[2:3], exec
	s_cselect_b32 s98, s99, s98
	s_ashr_i32 s99, s98, 31
	s_lshl_b64 s[98:99], s[98:99], 11
	v_lshl_add_u64 v[174:175], v[110:111], 0, s[98:99]
	global_load_dwordx4 v[160:163], v[174:175], off
	global_load_dwordx4 v[164:167], v[174:175], off offset:1024
	s_waitcnt vmcnt(0)
	s_branch .LBB0_38
.LBB0_37:
	s_add_i32 s56, s56, 4
	s_cmp_ge_i32 s56, s57
	s_cbranch_scc1 .LBB0_134

.LBB0_144:
	s_or_b64 exec, exec, s[8:9]
	s_add_i32 s98, s0, 0
	s_mul_hi_i32 s99, s98, 0x38e38e39
	s_lshr_b32 s100, s99, 31
	s_ashr_i32 s99, s99, 9
	s_add_i32 s99, s99, s100
	s_mulk_i32 s99, 0x900
	s_sub_i32 s98, s98, s99
	s_add_i32 s99, s98, 0xffffff00
	s_and_b32 s100, s98, 63
	s_ashr_i32 s99, s99, 6
	v_mov_b32_e32 v164, s100
	v_mov_b32_e32 v165, s99
	v_cndmask_b32_e64 v164, v164, v165, s[6:7]
	v_lshlrev_b32_e32 v164, 5, v164
	s_cmpk_gt_i32 s98, 0xff
	s_cselect_b64 vcc, -1, 0
	v_cndmask_b32_e32 v164, 0, v164, vcc
	v_ashrrev_i32_e32 v165, 31, v164
	v_lshl_add_u64 v[164:165], v[164:165], 3, v[58:59]
	global_load_dwordx4 v[100:103], v[164:165], off
	global_load_dwordx4 v[104:107], v[164:165], off offset:16
	global_load_dwordx4 v[108:111], v[164:165], off offset:32
	global_load_dwordx4 v[112:115], v[164:165], off offset:48
	global_load_dwordx4 v[116:119], v[164:165], off offset:64
	global_load_dwordx4 v[120:123], v[164:165], off offset:80
	global_load_dwordx4 v[124:127], v[164:165], off offset:96
	global_load_dwordx4 v[128:131], v[164:165], off offset:112
	s_add_i32 s98, s0, 1
	s_mul_hi_i32 s99, s98, 0x38e38e39
	s_lshr_b32 s100, s99, 31
	s_ashr_i32 s99, s99, 9
	s_add_i32 s99, s99, s100
	s_mulk_i32 s99, 0x900
	s_sub_i32 s98, s98, s99
	s_add_i32 s99, s98, 0xffffff00
	s_and_b32 s100, s98, 63
	s_ashr_i32 s99, s99, 6
	v_mov_b32_e32 v166, s100
	v_mov_b32_e32 v167, s99
	v_cndmask_b32_e64 v166, v166, v167, s[6:7]
	v_lshlrev_b32_e32 v166, 5, v166
	s_cmpk_gt_i32 s98, 0xff
	s_cselect_b64 vcc, -1, 0
	v_cndmask_b32_e32 v166, 0, v166, vcc
	v_ashrrev_i32_e32 v167, 31, v166
	v_lshl_add_u64 v[166:167], v[166:167], 3, v[58:59]
	global_load_dwordx4 v[132:135], v[166:167], off
	global_load_dwordx4 v[136:139], v[166:167], off offset:16
	global_load_dwordx4 v[140:143], v[166:167], off offset:32
	global_load_dwordx4 v[144:147], v[166:167], off offset:48
	global_load_dwordx4 v[148:151], v[166:167], off offset:64
	global_load_dwordx4 v[152:155], v[166:167], off offset:80
	global_load_dwordx4 v[156:159], v[166:167], off offset:96
	global_load_dwordx4 v[160:163], v[166:167], off offset:112
	s_waitcnt vmcnt(17)
	v_lshlrev_b32_e32 v68, 16, v55
	v_and_b32_e32 v69, 0xffff0000, v55
	s_mov_b32 s8, 0x3d372713
	v_pk_mul_f32 v[70:71], v[68:69], s[8:9] op_sel_hi:[1,0]
	s_mov_b32 s12, 0x3f4c422a
	v_pk_mul_f32 v[70:71], v[70:71], v[68:69]
	s_mov_b32 s1, 0x800000
	v_pk_fma_f32 v[70:71], v[70:71], v[68:69], v[68:69]
	v_pk_mul_f32 v[68:69], v[68:69], 0.5 op_sel_hi:[1,0]
	v_pk_mul_f32 v[70:71], v[70:71], s[12:13] op_sel_hi:[1,0]
	s_nop 0
	v_mul_f32_e64 v55, |v70|, -2.0
	v_mul_f32_e32 v55, 0x3fb8aa3b, v55
	v_exp_f32_e32 v80, v55
	v_mul_f32_e64 v55, |v71|, -2.0
	v_mul_f32_e32 v55, 0x3fb8aa3b, v55
	v_exp_f32_e32 v81, v55
	v_add_f32_e32 v55, 1.0, v80
	v_rcp_f32_e32 v82, v55
	v_cmp_gt_f32_e32 vcc, 0, v71
	v_add_f32_e32 v55, 1.0, v81
	v_rcp_f32_e32 v83, v55
	v_pk_add_f32 v[80:81], v[80:81], 1.0 op_sel_hi:[1,0] neg_lo:[1,0] neg_hi:[1,0]
	s_nop 0
	v_pk_mul_f32 v[80:81], v[80:81], v[82:83]
	v_lshlrev_b32_e32 v82, 16, v54
	v_and_b32_e32 v83, 0xffff0000, v54
	v_pk_mul_f32 v[84:85], v[82:83], s[8:9] op_sel_hi:[1,0]
	v_cndmask_b32_e64 v55, v81, -v81, vcc
	v_pk_mul_f32 v[84:85], v[84:85], v[82:83]
	v_cmp_gt_f32_e32 vcc, 0, v70
	v_pk_fma_f32 v[84:85], v[84:85], v[82:83], v[82:83]
	v_pk_mul_f32 v[82:83], v[82:83], 0.5 op_sel_hi:[1,0]
	v_pk_mul_f32 v[84:85], v[84:85], s[12:13] op_sel_hi:[1,0]
	s_nop 0
	v_mul_f32_e64 v54, |v84|, -2.0
	v_mul_f32_e32 v54, 0x3fb8aa3b, v54
	v_exp_f32_e32 v86, v54
	v_mul_f32_e64 v54, |v85|, -2.0
	v_mul_f32_e32 v54, 0x3fb8aa3b, v54
	v_exp_f32_e32 v87, v54
	v_add_f32_e32 v70, 1.0, v86
	v_rcp_f32_e32 v70, v70
	v_cndmask_b32_e64 v54, v80, -v80, vcc
	v_add_f32_e32 v71, 1.0, v87
	v_rcp_f32_e32 v71, v71
	v_pk_add_f32 v[86:87], v[86:87], 1.0 op_sel_hi:[1,0] neg_lo:[1,0] neg_hi:[1,0]
	v_cmp_gt_f32_e32 vcc, 0, v85
	v_pk_add_f32 v[54:55], v[54:55], 1.0 op_sel_hi:[1,0]
	v_pk_mul_f32 v[70:71], v[86:87], v[70:71]
	v_lshlrev_b32_e32 v86, 16, v53
	v_and_b32_e32 v87, 0xffff0000, v53
	v_pk_mul_f32 v[88:89], v[86:87], s[8:9] op_sel_hi:[1,0]
	v_cndmask_b32_e64 v71, v71, -v71, vcc
	v_pk_mul_f32 v[88:89], v[88:89], v[86:87]
	v_cmp_gt_f32_e32 vcc, 0, v84
	v_pk_fma_f32 v[88:89], v[88:89], v[86:87], v[86:87]
	v_pk_mul_f32 v[86:87], v[86:87], 0.5 op_sel_hi:[1,0]
	v_pk_mul_f32 v[88:89], v[88:89], s[12:13] op_sel_hi:[1,0]
	v_cndmask_b32_e64 v70, v70, -v70, vcc
	v_mul_f32_e64 v53, |v88|, -2.0
	v_mul_f32_e32 v53, 0x3fb8aa3b, v53
	v_exp_f32_e32 v90, v53
	v_mul_f32_e64 v53, |v89|, -2.0
	v_mul_f32_e32 v53, 0x3fb8aa3b, v53
	v_exp_f32_e32 v91, v53
	v_add_f32_e32 v53, 1.0, v90
	v_rcp_f32_e32 v84, v53
	v_cmp_gt_f32_e32 vcc, 0, v89
	v_add_f32_e32 v53, 1.0, v91
	v_rcp_f32_e32 v85, v53
	v_pk_add_f32 v[90:91], v[90:91], 1.0 op_sel_hi:[1,0] neg_lo:[1,0] neg_hi:[1,0]
	v_pk_add_f32 v[70:71], v[70:71], 1.0 op_sel_hi:[1,0]
	v_pk_mul_f32 v[80:81], v[68:69], v[54:55]
	v_pk_mul_f32 v[84:85], v[90:91], v[84:85]
	v_lshlrev_b32_e32 v90, 16, v52
	v_and_b32_e32 v91, 0xffff0000, v52
	v_pk_mul_f32 v[94:95], v[90:91], s[8:9] op_sel_hi:[1,0]
	v_cndmask_b32_e64 v53, v85, -v85, vcc
	v_pk_mul_f32 v[94:95], v[94:95], v[90:91]
	v_cmp_gt_f32_e32 vcc, 0, v88
	v_pk_fma_f32 v[94:95], v[94:95], v[90:91], v[90:91]
	v_pk_mul_f32 v[90:91], v[90:91], 0.5 op_sel_hi:[1,0]
	v_pk_mul_f32 v[94:95], v[94:95], s[12:13] op_sel_hi:[1,0]
	v_pk_mul_f32 v[92:93], v[82:83], v[70:71]
	v_mul_f32_e64 v52, |v94|, -2.0
	v_mul_f32_e32 v52, 0x3fb8aa3b, v52
	v_exp_f32_e32 v96, v52
	v_mul_f32_e64 v52, |v95|, -2.0
	v_mul_f32_e32 v52, 0x3fb8aa3b, v52
	v_exp_f32_e32 v97, v52
	v_add_f32_e32 v79, 1.0, v96
	v_cndmask_b32_e64 v52, v84, -v84, vcc
	v_rcp_f32_e32 v84, v79
	v_add_f32_e32 v79, 1.0, v97
	v_rcp_f32_e32 v85, v79
	v_pk_add_f32 v[96:97], v[96:97], 1.0 op_sel_hi:[1,0] neg_lo:[1,0] neg_hi:[1,0]
	v_cmp_gt_f32_e32 vcc, 0, v95
	v_pk_add_f32 v[52:53], v[52:53], 1.0 op_sel_hi:[1,0]
	v_pk_mul_f32 v[84:85], v[96:97], v[84:85]
	v_pk_mul_f32 v[88:89], v[86:87], v[52:53]
	v_cndmask_b32_e64 v85, v85, -v85, vcc
	v_cmp_gt_f32_e32 vcc, 0, v94
	s_nop 1
	v_cndmask_b32_e64 v84, v84, -v84, vcc
	v_pk_add_f32 v[84:85], v[84:85], 1.0 op_sel_hi:[1,0]
	s_nop 0
	v_pk_mul_f32 v[94:95], v[90:91], v[84:85]
	s_nop 0
	v_add_f32_e32 v79, 0, v94
	v_add_f32_e32 v79, v95, v79
	v_add_f32_e32 v79, v88, v79
	v_add_f32_e32 v79, v89, v79
	v_add_f32_e32 v79, v92, v79
	v_add_f32_e32 v79, v93, v79
	v_add_f32_e32 v79, v80, v79
	v_add_f32_e32 v79, v81, v79
	s_nop 1
	v_add_f32_dpp v79, v79, v79 quad_perm:[1,0,3,2] row_mask:0xf bank_mask:0xf
	s_nop 1
	v_add_f32_dpp v79, v79, v79 quad_perm:[2,3,0,1] row_mask:0xf bank_mask:0xf
	s_nop 1
	v_add_f32_dpp v79, v79, v79 row_half_mirror row_mask:0xf bank_mask:0xf
	s_nop 1
	v_add_f32_dpp v79, v79, v79 row_mirror row_mask:0xf bank_mask:0xf
	v_mov_b32_e32 v80, v79
	s_nop 1
	v_permlane16_swap_b32_e32 v80, v79
	v_add_f32_e32 v79, v79, v80
	v_mov_b32_e32 v80, v79
	s_nop 1
	v_permlane32_swap_b32_e32 v80, v79
	v_add_f32_e32 v79, v79, v80
	v_mul_f32_e32 v80, 0x3b000000, v79
	v_pk_fma_f32 v[84:85], v[90:91], v[84:85], v[80:81] op_sel_hi:[1,1,0] neg_lo:[0,0,1] neg_hi:[0,0,1]
	v_pk_fma_f32 v[52:53], v[86:87], v[52:53], v[80:81] op_sel_hi:[1,1,0] neg_lo:[0,0,1] neg_hi:[0,0,1]
	v_pk_mul_f32 v[88:89], v[84:85], v[84:85]
	v_pk_mul_f32 v[86:87], v[52:53], v[52:53]
	v_add_f32_e32 v79, v88, v89
	v_pk_fma_f32 v[70:71], v[82:83], v[70:71], v[80:81] op_sel_hi:[1,1,0] neg_lo:[0,0,1] neg_hi:[0,0,1]
	v_add_f32_e32 v79, v86, v79
	v_pk_mul_f32 v[82:83], v[70:71], v[70:71]
	v_add_f32_e32 v79, v87, v79
	v_pk_fma_f32 v[54:55], v[68:69], v[54:55], v[80:81] op_sel_hi:[1,1,0] neg_lo:[0,0,1] neg_hi:[0,0,1]
	v_add_f32_e32 v79, v82, v79
	v_pk_mul_f32 v[68:69], v[54:55], v[54:55]
	v_add_f32_e32 v79, v83, v79
	v_add_f32_e32 v68, v68, v79
	v_add_f32_e32 v68, v69, v68
	s_nop 1
	v_add_f32_dpp v68, v68, v68 quad_perm:[1,0,3,2] row_mask:0xf bank_mask:0xf
	s_nop 1
	v_add_f32_dpp v68, v68, v68 quad_perm:[2,3,0,1] row_mask:0xf bank_mask:0xf
	s_nop 1
	v_add_f32_dpp v68, v68, v68 row_half_mirror row_mask:0xf bank_mask:0xf
	s_nop 1
	v_add_f32_dpp v68, v68, v68 row_mirror row_mask:0xf bank_mask:0xf
	v_mov_b32_e32 v69, v68
	s_nop 1
	v_permlane16_swap_b32_e32 v69, v68
	v_add_f32_e32 v68, v68, v69
	v_mov_b32_e32 v69, v68
	s_nop 1
	v_permlane32_swap_b32_e32 v69, v68
	v_add_f32_e32 v68, v68, v69
	v_fmamk_f32 v68, v68, 0x3b000000, v225
	v_mul_f32_e32 v69, 0x4b800000, v68
	v_cmp_gt_f32_e32 vcc, s1, v68
	s_nop 1
	v_cndmask_b32_e32 v68, v68, v69, vcc
	v_rsq_f32_e32 v68, v68
	s_nop 0
	v_mul_f32_e32 v69, 0x45800000, v68
	v_cndmask_b32_e32 v68, v68, v69, vcc
	v_pk_mul_f32 v[52:53], v[52:53], v[68:69] op_sel_hi:[1,0]
	v_pk_mul_f32 v[80:81], v[84:85], v[68:69] op_sel_hi:[1,0]
	v_pk_fma_f32 v[82:83], v[10:11], v[52:53], v[14:15]
	v_pk_mul_f32 v[52:53], v[70:71], v[68:69] op_sel_hi:[1,0]
	v_pk_fma_f32 v[80:81], v[8:9], v[80:81], v[12:13]
	v_pk_fma_f32 v[70:71], v[0:1], v[52:53], v[4:5]
	v_pk_mul_f32 v[52:53], v[54:55], v[68:69] op_sel_hi:[1,0]
	v_cvt_pk_bf16_f32 v54, v70, v71
	v_pk_fma_f32 v[68:69], v[2:3], v[52:53], v[6:7]
	v_cvt_pk_bf16_f32 v52, v80, v81
	v_cvt_pk_bf16_f32 v53, v82, v83
	v_cvt_pk_bf16_f32 v55, v68, v69
	global_store_dwordx4 v[66:67], v[52:55], off
	s_and_saveexec_b64 s[12:13], s[4:5]
	s_cbranch_execz .LBB0_162
	v_lshlrev_b32_e32 v52, 16, v48
	v_and_b32_e32 v53, 0xffff0000, v48
	v_pk_mul_f32 v[54:55], v[52:53], v[52:53]
	v_lshlrev_b32_e32 v48, 16, v49
	v_and_b32_e32 v49, 0xffff0000, v49
	v_pk_mul_f32 v[66:67], v[48:49], v[48:49]
	v_add_f32_e32 v54, v54, v55
	v_lshlrev_b32_e32 v68, 16, v50
	v_and_b32_e32 v69, 0xffff0000, v50
	v_add_f32_e32 v54, v66, v54
	v_pk_mul_f32 v[70:71], v[68:69], v[68:69]
	v_add_f32_e32 v54, v67, v54
	v_lshlrev_b32_e32 v50, 16, v51
	v_and_b32_e32 v51, 0xffff0000, v51
	v_add_f32_e32 v54, v70, v54
	v_pk_mul_f32 v[80:81], v[50:51], v[50:51]
	v_add_f32_e32 v54, v71, v54
	v_lshlrev_b32_e32 v82, 16, v44
	v_and_b32_e32 v83, 0xffff0000, v44
	v_add_f32_e32 v54, v80, v54
	v_pk_mul_f32 v[84:85], v[82:83], v[82:83]
	v_add_f32_e32 v54, v81, v54
	v_lshlrev_b32_e32 v86, 16, v45
	v_and_b32_e32 v87, 0xffff0000, v45
	v_add_f32_e32 v54, v84, v54
	v_pk_mul_f32 v[44:45], v[86:87], v[86:87]
	v_add_f32_e32 v54, v85, v54
	v_lshlrev_b32_e32 v88, 16, v46
	v_and_b32_e32 v89, 0xffff0000, v46
	v_add_f32_e32 v44, v44, v54
	v_pk_mul_f32 v[90:91], v[88:89], v[88:89]
	v_add_f32_e32 v44, v45, v44
	v_lshlrev_b32_e32 v92, 16, v47
	v_and_b32_e32 v93, 0xffff0000, v47
	v_add_f32_e32 v44, v90, v44
	v_pk_mul_f32 v[46:47], v[92:93], v[92:93]
	v_add_f32_e32 v44, v91, v44
	v_add_f32_e32 v44, v46, v44
	v_add_f32_e32 v44, v47, v44
	s_mov_b32 s9, 0x800000
	s_mul_hi_i32 s1, s0, 0x38e38e39
	s_lshr_b32 s8, s1, 31
	s_ashr_i32 s1, s1, 9
	s_nop 1
	v_add_f32_dpp v44, v44, v44 quad_perm:[1,0,3,2] row_mask:0xf bank_mask:0xf
	s_add_i32 s1, s1, s8
	s_mulk_i32 s1, 0x900
	s_sub_i32 s1, s0, s1
	s_cmpk_gt_i32 s1, 0xff
	s_nop 1
	v_add_f32_dpp v44, v44, v44 quad_perm:[2,3,0,1] row_mask:0xf bank_mask:0xf
	s_nop 1
	v_add_f32_dpp v44, v44, v44 row_half_mirror row_mask:0xf bank_mask:0xf
	v_fmamk_f32 v44, v44, 0x3c000000, v225
	v_mul_f32_e32 v45, 0x4b800000, v44
	v_cmp_gt_f32_e32 vcc, s9, v44
	s_nop 1
	v_cndmask_b32_e32 v44, v44, v45, vcc
	v_rsq_f32_e32 v44, v44
	s_nop 0
	v_mul_f32_e32 v45, 0x45800000, v44
	v_cndmask_b32_e32 v70, v44, v45, vcc
	v_pk_mul_f32 v[44:45], v[70:71], v[52:53] op_sel_hi:[0,1]
	v_pk_mul_f32 v[52:53], v[28:29], v[44:45]
	v_pk_mul_f32 v[44:45], v[70:71], v[48:49] op_sel_hi:[0,1]
	v_pk_mul_f32 v[54:55], v[30:31], v[44:45]
	v_pk_mul_f32 v[44:45], v[70:71], v[68:69] op_sel_hi:[0,1]
	s_cselect_b64 vcc, -1, 0
	s_add_i32 s8, s1, 0xffffff00
	v_pk_mul_f32 v[66:67], v[24:25], v[44:45]
	v_pk_mul_f32 v[44:45], v[70:71], v[50:51] op_sel_hi:[0,1]
	v_pk_mul_f32 v[48:49], v[70:71], v[88:89] op_sel_hi:[0,1]
	s_and_b32 s9, s1, 63
	s_ashr_i32 s8, s8, 6
	v_pk_mul_f32 v[68:69], v[26:27], v[44:45]
	v_pk_mul_f32 v[44:45], v[70:71], v[82:83] op_sel_hi:[0,1]
	v_pk_mul_f32 v[46:47], v[70:71], v[86:87] op_sel_hi:[0,1]
	v_pk_mul_f32 v[50:51], v[16:17], v[48:49]
	v_pk_mul_f32 v[48:49], v[70:71], v[92:93] op_sel_hi:[0,1]
	v_mov_b32_e32 v70, s9
	v_mov_b32_e32 v71, s8
	v_cndmask_b32_e64 v70, v70, v71, s[6:7]
	v_mov_b32_dpp v80, v52 quad_perm:[2,3,0,1] row_mask:0xf bank_mask:0xf
	v_mov_b32_dpp v79, v53 quad_perm:[2,3,0,1] row_mask:0xf bank_mask:0xf
	v_lshlrev_b32_e32 v70, 5, v70
	v_cndmask_b32_e32 v70, 0, v70, vcc
	v_ashrrev_i32_e32 v71, 31, v70
	v_pk_mul_f32 v[44:45], v[20:21], v[44:45]
	v_pk_mul_f32 v[46:47], v[22:23], v[46:47]
	v_pk_mul_f32 v[48:49], v[18:19], v[48:49]
	s_cmpk_lt_i32 s1, 0x100
	v_lshl_add_u64 v[70:71], v[70:71], 3, v[58:59]
	s_waitcnt vmcnt(0)
	s_cbranch_scc1 .LBB0_147
	s_waitcnt lgkmcnt(1)
	v_mul_f32_e32 v86, v72, v80
	s_waitcnt lgkmcnt(0)
	v_mul_f32_e32 v81, v72, v79
	v_mov_b32_e32 v80, v53
	s_waitcnt vmcnt(0)
	v_pk_mul_f32 v[80:81], v[80:81], v[102:103]
	v_mul_f32_e32 v52, v52, v100
	v_mul_f32_e32 v82, v86, v101
	v_mov_b32_e32 v53, v81
	v_mov_b32_e32 v83, v80
	v_pk_add_f32 v[52:53], v[52:53], v[82:83]

.LBB0_162:
	s_or_b64 exec, exec, s[12:13]
	s_waitcnt vmcnt(1)
	v_lshlrev_b32_e32 v46, 16, v43
	v_and_b32_e32 v47, 0xffff0000, v43
	s_mov_b32 s8, 0x3d372713
	v_pk_mul_f32 v[48:49], v[46:47], s[8:9] op_sel_hi:[1,0]
	s_mov_b32 s12, 0x3f4c422a
	v_pk_mul_f32 v[48:49], v[48:49], v[46:47]
	s_mov_b32 s1, 0x800000
	v_pk_fma_f32 v[48:49], v[48:49], v[46:47], v[46:47]
	v_pk_mul_f32 v[46:47], v[46:47], 0.5 op_sel_hi:[1,0]
	v_pk_mul_f32 v[48:49], v[48:49], s[12:13] op_sel_hi:[1,0]
	v_lshl_add_u64 v[44:45], s[2:3], 0, v[192:193]
	v_mul_f32_e64 v43, |v48|, -2.0
	v_mul_f32_e32 v43, 0x3fb8aa3b, v43
	v_exp_f32_e32 v50, v43
	v_mul_f32_e64 v43, |v49|, -2.0
	v_mul_f32_e32 v43, 0x3fb8aa3b, v43
	v_exp_f32_e32 v51, v43
	v_add_f32_e32 v43, 1.0, v50
	v_rcp_f32_e32 v52, v43
	v_cmp_gt_f32_e32 vcc, 0, v49
	v_add_f32_e32 v43, 1.0, v51
	v_rcp_f32_e32 v53, v43
	v_pk_add_f32 v[50:51], v[50:51], 1.0 op_sel_hi:[1,0] neg_lo:[1,0] neg_hi:[1,0]
	s_nop 0
	v_pk_mul_f32 v[50:51], v[50:51], v[52:53]
	v_lshlrev_b32_e32 v52, 16, v42
	v_and_b32_e32 v53, 0xffff0000, v42
	v_pk_mul_f32 v[54:55], v[52:53], s[8:9] op_sel_hi:[1,0]
	v_cndmask_b32_e64 v43, v51, -v51, vcc
	v_pk_mul_f32 v[54:55], v[54:55], v[52:53]
	v_cmp_gt_f32_e32 vcc, 0, v48
	v_pk_fma_f32 v[54:55], v[54:55], v[52:53], v[52:53]
	v_pk_mul_f32 v[52:53], v[52:53], 0.5 op_sel_hi:[1,0]
	v_pk_mul_f32 v[54:55], v[54:55], s[12:13] op_sel_hi:[1,0]
	s_nop 0
	v_mul_f32_e64 v42, |v54|, -2.0
	v_mul_f32_e32 v42, 0x3fb8aa3b, v42
	v_exp_f32_e32 v64, v42
	v_mul_f32_e64 v42, |v55|, -2.0
	v_mul_f32_e32 v42, 0x3fb8aa3b, v42
	v_exp_f32_e32 v65, v42
	v_add_f32_e32 v48, 1.0, v64
	v_rcp_f32_e32 v48, v48
	v_cndmask_b32_e64 v42, v50, -v50, vcc
	v_add_f32_e32 v49, 1.0, v65
	v_rcp_f32_e32 v49, v49
	v_pk_add_f32 v[64:65], v[64:65], 1.0 op_sel_hi:[1,0] neg_lo:[1,0] neg_hi:[1,0]
	v_cmp_gt_f32_e32 vcc, 0, v55
	v_pk_add_f32 v[42:43], v[42:43], 1.0 op_sel_hi:[1,0]
	v_pk_mul_f32 v[48:49], v[64:65], v[48:49]
	v_lshlrev_b32_e32 v64, 16, v41
	v_and_b32_e32 v65, 0xffff0000, v41
	v_pk_mul_f32 v[66:67], v[64:65], s[8:9] op_sel_hi:[1,0]
	v_cndmask_b32_e64 v49, v49, -v49, vcc
	v_pk_mul_f32 v[66:67], v[66:67], v[64:65]
	v_cmp_gt_f32_e32 vcc, 0, v54
	v_pk_fma_f32 v[66:67], v[66:67], v[64:65], v[64:65]
	v_pk_mul_f32 v[64:65], v[64:65], 0.5 op_sel_hi:[1,0]
	v_pk_mul_f32 v[66:67], v[66:67], s[12:13] op_sel_hi:[1,0]
	v_cndmask_b32_e64 v48, v48, -v48, vcc
	v_mul_f32_e64 v41, |v66|, -2.0
	v_mul_f32_e32 v41, 0x3fb8aa3b, v41
	v_exp_f32_e32 v68, v41
	v_mul_f32_e64 v41, |v67|, -2.0
	v_mul_f32_e32 v41, 0x3fb8aa3b, v41
	v_exp_f32_e32 v69, v41
	v_add_f32_e32 v41, 1.0, v68
	v_rcp_f32_e32 v54, v41
	v_cmp_gt_f32_e32 vcc, 0, v67
	v_add_f32_e32 v41, 1.0, v69
	v_rcp_f32_e32 v55, v41
	v_pk_add_f32 v[68:69], v[68:69], 1.0 op_sel_hi:[1,0] neg_lo:[1,0] neg_hi:[1,0]
	v_pk_add_f32 v[48:49], v[48:49], 1.0 op_sel_hi:[1,0]
	v_pk_mul_f32 v[50:51], v[46:47], v[42:43]
	v_pk_mul_f32 v[54:55], v[68:69], v[54:55]
	v_lshlrev_b32_e32 v68, 16, v40
	v_and_b32_e32 v69, 0xffff0000, v40
	s_waitcnt lgkmcnt(1)
	v_pk_mul_f32 v[80:81], v[68:69], s[8:9] op_sel_hi:[1,0]
	v_cndmask_b32_e64 v41, v55, -v55, vcc
	v_pk_mul_f32 v[80:81], v[80:81], v[68:69]
	v_cmp_gt_f32_e32 vcc, 0, v66
	v_pk_fma_f32 v[80:81], v[80:81], v[68:69], v[68:69]
	v_pk_mul_f32 v[68:69], v[68:69], 0.5 op_sel_hi:[1,0]
	v_pk_mul_f32 v[80:81], v[80:81], s[12:13] op_sel_hi:[1,0]
	v_pk_mul_f32 v[70:71], v[52:53], v[48:49]
	v_mul_f32_e64 v40, |v80|, -2.0
	v_mul_f32_e32 v40, 0x3fb8aa3b, v40
	v_exp_f32_e32 v82, v40
	v_mul_f32_e64 v40, |v81|, -2.0
	v_mul_f32_e32 v40, 0x3fb8aa3b, v40
	v_exp_f32_e32 v83, v40
	v_cndmask_b32_e64 v40, v54, -v54, vcc
	v_add_f32_e32 v54, 1.0, v82
	v_rcp_f32_e32 v54, v54
	v_add_f32_e32 v55, 1.0, v83
	v_rcp_f32_e32 v55, v55
	v_pk_add_f32 v[82:83], v[82:83], 1.0 op_sel_hi:[1,0] neg_lo:[1,0] neg_hi:[1,0]
	v_cmp_gt_f32_e32 vcc, 0, v81
	v_pk_add_f32 v[40:41], v[40:41], 1.0 op_sel_hi:[1,0]
	v_pk_mul_f32 v[54:55], v[82:83], v[54:55]
	v_pk_mul_f32 v[66:67], v[64:65], v[40:41]
	v_cndmask_b32_e64 v55, v55, -v55, vcc
	v_cmp_gt_f32_e32 vcc, 0, v80
	s_nop 1
	v_cndmask_b32_e64 v54, v54, -v54, vcc
	v_pk_add_f32 v[54:55], v[54:55], 1.0 op_sel_hi:[1,0]
	s_nop 0
	v_pk_mul_f32 v[80:81], v[68:69], v[54:55]
	s_waitcnt lgkmcnt(0)
	v_add_f32_e32 v79, 0, v80
	v_add_f32_e32 v79, v81, v79
	v_add_f32_e32 v66, v66, v79
	v_add_f32_e32 v66, v67, v66
	v_add_f32_e32 v66, v70, v66
	v_add_f32_e32 v66, v71, v66
	v_add_f32_e32 v50, v50, v66
	v_add_f32_e32 v50, v51, v50
	s_nop 1
	v_add_f32_dpp v50, v50, v50 quad_perm:[1,0,3,2] row_mask:0xf bank_mask:0xf
	s_nop 1
	v_add_f32_dpp v50, v50, v50 quad_perm:[2,3,0,1] row_mask:0xf bank_mask:0xf
	s_nop 1
	v_add_f32_dpp v50, v50, v50 row_half_mirror row_mask:0xf bank_mask:0xf
	s_nop 1
	v_add_f32_dpp v50, v50, v50 row_mirror row_mask:0xf bank_mask:0xf
	v_mov_b32_e32 v51, v50
	s_nop 1
	v_permlane16_swap_b32_e32 v51, v50
	v_add_f32_e32 v50, v50, v51
	v_mov_b32_e32 v51, v50
	s_nop 1
	v_permlane32_swap_b32_e32 v51, v50
	v_add_f32_e32 v50, v50, v51
	v_mul_f32_e32 v50, 0x3b000000, v50
	v_pk_fma_f32 v[54:55], v[68:69], v[54:55], v[50:51] op_sel_hi:[1,1,0] neg_lo:[0,0,1] neg_hi:[0,0,1]
	v_pk_fma_f32 v[40:41], v[64:65], v[40:41], v[50:51] op_sel_hi:[1,1,0] neg_lo:[0,0,1] neg_hi:[0,0,1]
	v_pk_mul_f32 v[66:67], v[54:55], v[54:55]
	v_pk_mul_f32 v[64:65], v[40:41], v[40:41]
	v_pk_fma_f32 v[48:49], v[52:53], v[48:49], v[50:51] op_sel_hi:[1,1,0] neg_lo:[0,0,1] neg_hi:[0,0,1]
	v_pk_fma_f32 v[42:43], v[46:47], v[42:43], v[50:51] op_sel_hi:[1,1,0] neg_lo:[0,0,1] neg_hi:[0,0,1]
	v_add_f32_e32 v50, v66, v67
	v_add_f32_e32 v50, v64, v50
	v_pk_mul_f32 v[52:53], v[48:49], v[48:49]
	v_add_f32_e32 v50, v65, v50
	v_add_f32_e32 v50, v52, v50
	v_pk_mul_f32 v[46:47], v[42:43], v[42:43]
	v_add_f32_e32 v50, v53, v50
	v_add_f32_e32 v46, v46, v50
	v_add_f32_e32 v46, v47, v46
	s_nop 1
	v_add_f32_dpp v46, v46, v46 quad_perm:[1,0,3,2] row_mask:0xf bank_mask:0xf
	s_nop 1
	v_add_f32_dpp v46, v46, v46 quad_perm:[2,3,0,1] row_mask:0xf bank_mask:0xf
	s_nop 1
	v_add_f32_dpp v46, v46, v46 row_half_mirror row_mask:0xf bank_mask:0xf
	s_nop 1
	v_add_f32_dpp v46, v46, v46 row_mirror row_mask:0xf bank_mask:0xf
	v_mov_b32_e32 v47, v46
	s_nop 1
	v_permlane16_swap_b32_e32 v47, v46
	v_add_f32_e32 v46, v46, v47
	v_mov_b32_e32 v47, v46
	s_nop 1
	v_permlane32_swap_b32_e32 v47, v46
	v_add_f32_e32 v46, v46, v47
	v_fmamk_f32 v46, v46, 0x3b000000, v225
	v_mul_f32_e32 v47, 0x4b800000, v46
	v_cmp_gt_f32_e32 vcc, s1, v46
	s_nop 1
	v_cndmask_b32_e32 v46, v46, v47, vcc
	v_rsq_f32_e32 v46, v46
	s_nop 0
	v_mul_f32_e32 v47, 0x45800000, v46
	v_cndmask_b32_e32 v46, v46, v47, vcc
	v_pk_mul_f32 v[40:41], v[40:41], v[46:47] op_sel_hi:[1,0]
	v_pk_mul_f32 v[50:51], v[54:55], v[46:47] op_sel_hi:[1,0]
	v_pk_fma_f32 v[52:53], v[10:11], v[40:41], v[14:15]
	v_pk_mul_f32 v[40:41], v[48:49], v[46:47] op_sel_hi:[1,0]
	v_pk_fma_f32 v[50:51], v[8:9], v[50:51], v[12:13]
	v_pk_fma_f32 v[48:49], v[0:1], v[40:41], v[4:5]
	v_pk_mul_f32 v[40:41], v[42:43], v[46:47] op_sel_hi:[1,0]
	v_cvt_pk_bf16_f32 v42, v48, v49
	v_pk_fma_f32 v[46:47], v[2:3], v[40:41], v[6:7]
	v_cvt_pk_bf16_f32 v40, v50, v51
	v_cvt_pk_bf16_f32 v41, v52, v53
	v_cvt_pk_bf16_f32 v43, v46, v47
	global_store_dwordx4 v[44:45], v[40:43], off offset:1024
	s_and_saveexec_b64 s[12:13], s[4:5]
	s_cbranch_execz .LBB0_139
	v_lshlrev_b32_e32 v40, 16, v36
	v_and_b32_e32 v41, 0xffff0000, v36
	v_pk_mul_f32 v[42:43], v[40:41], v[40:41]
	v_lshlrev_b32_e32 v36, 16, v37
	v_and_b32_e32 v37, 0xffff0000, v37
	v_pk_mul_f32 v[44:45], v[36:37], v[36:37]
	v_add_f32_e32 v42, v42, v43
	v_lshlrev_b32_e32 v46, 16, v38
	v_and_b32_e32 v47, 0xffff0000, v38
	v_add_f32_e32 v42, v44, v42
	v_pk_mul_f32 v[48:49], v[46:47], v[46:47]
	v_add_f32_e32 v42, v45, v42
	v_lshlrev_b32_e32 v38, 16, v39
	v_and_b32_e32 v39, 0xffff0000, v39
	v_add_f32_e32 v42, v48, v42
	v_pk_mul_f32 v[50:51], v[38:39], v[38:39]
	v_add_f32_e32 v42, v49, v42
	v_lshlrev_b32_e32 v52, 16, v32
	v_and_b32_e32 v53, 0xffff0000, v32
	v_add_f32_e32 v42, v50, v42
	v_pk_mul_f32 v[54:55], v[52:53], v[52:53]
	v_add_f32_e32 v42, v51, v42
	v_lshlrev_b32_e32 v64, 16, v33
	v_and_b32_e32 v65, 0xffff0000, v33
	v_add_f32_e32 v42, v54, v42
	v_pk_mul_f32 v[32:33], v[64:65], v[64:65]
	v_add_f32_e32 v42, v55, v42
	v_lshlrev_b32_e32 v66, 16, v34
	v_and_b32_e32 v67, 0xffff0000, v34
	v_add_f32_e32 v32, v32, v42
	v_pk_mul_f32 v[68:69], v[66:67], v[66:67]
	v_add_f32_e32 v32, v33, v32
	v_lshlrev_b32_e32 v70, 16, v35
	v_and_b32_e32 v71, 0xffff0000, v35
	v_add_f32_e32 v32, v68, v32
	v_pk_mul_f32 v[34:35], v[70:71], v[70:71]
	v_add_f32_e32 v32, v69, v32
	v_add_f32_e32 v32, v34, v32
	v_add_f32_e32 v32, v35, v32
	s_mov_b32 s9, 0x800000
	s_mul_hi_i32 s1, s10, 0x38e38e39
	s_lshr_b32 s8, s1, 31
	s_ashr_i32 s1, s1, 9
	s_nop 1
	v_add_f32_dpp v32, v32, v32 quad_perm:[1,0,3,2] row_mask:0xf bank_mask:0xf
	s_add_i32 s1, s1, s8
	s_mulk_i32 s1, 0x900
	s_sub_i32 s1, s10, s1
	s_cmpk_gt_i32 s1, 0xff
	s_nop 1
	v_add_f32_dpp v32, v32, v32 quad_perm:[2,3,0,1] row_mask:0xf bank_mask:0xf
	s_nop 1
	v_add_f32_dpp v32, v32, v32 row_half_mirror row_mask:0xf bank_mask:0xf
	v_fmamk_f32 v32, v32, 0x3c000000, v225
	v_mul_f32_e32 v33, 0x4b800000, v32
	v_cmp_gt_f32_e32 vcc, s9, v32
	s_nop 1
	v_cndmask_b32_e32 v32, v32, v33, vcc
	v_rsq_f32_e32 v32, v32
	s_nop 0
	v_mul_f32_e32 v33, 0x45800000, v32
	v_cndmask_b32_e32 v48, v32, v33, vcc
	v_pk_mul_f32 v[32:33], v[48:49], v[40:41] op_sel_hi:[0,1]
	v_pk_mul_f32 v[34:35], v[28:29], v[32:33]
	v_pk_mul_f32 v[32:33], v[48:49], v[36:37] op_sel_hi:[0,1]
	v_pk_mul_f32 v[42:43], v[30:31], v[32:33]
	v_pk_mul_f32 v[32:33], v[48:49], v[46:47] op_sel_hi:[0,1]
	s_cselect_b64 vcc, -1, 0
	s_add_i32 s8, s1, 0xffffff00
	v_pk_mul_f32 v[44:45], v[24:25], v[32:33]
	v_pk_mul_f32 v[32:33], v[48:49], v[38:39] op_sel_hi:[0,1]
	v_pk_mul_f32 v[38:39], v[48:49], v[66:67] op_sel_hi:[0,1]
	s_and_b32 s9, s1, 63
	s_ashr_i32 s8, s8, 6
	v_pk_mul_f32 v[46:47], v[26:27], v[32:33]
	v_pk_mul_f32 v[32:33], v[48:49], v[52:53] op_sel_hi:[0,1]
	v_pk_mul_f32 v[36:37], v[48:49], v[64:65] op_sel_hi:[0,1]
	v_pk_mul_f32 v[40:41], v[16:17], v[38:39]
	v_pk_mul_f32 v[38:39], v[48:49], v[70:71] op_sel_hi:[0,1]
	v_mov_b32_e32 v48, s9
	v_mov_b32_e32 v49, s8
	v_cndmask_b32_e64 v48, v48, v49, s[6:7]
	v_mov_b32_dpp v51, v34 quad_perm:[2,3,0,1] row_mask:0xf bank_mask:0xf
	v_mov_b32_dpp v50, v35 quad_perm:[2,3,0,1] row_mask:0xf bank_mask:0xf
	v_lshlrev_b32_e32 v48, 5, v48
	v_cndmask_b32_e32 v48, 0, v48, vcc
	v_ashrrev_i32_e32 v49, 31, v48
	v_pk_mul_f32 v[32:33], v[20:21], v[32:33]
	v_pk_mul_f32 v[36:37], v[22:23], v[36:37]
	v_pk_mul_f32 v[38:39], v[18:19], v[38:39]
	s_cmpk_lt_i32 s1, 0x100
	v_lshl_add_u64 v[48:49], v[48:49], 3, v[58:59]
	s_waitcnt vmcnt(0)
	s_cbranch_scc1 .LBB0_165
	s_waitcnt lgkmcnt(1)
	v_mul_f32_e32 v64, v72, v51
	s_waitcnt lgkmcnt(0)
	v_mul_f32_e32 v51, v72, v50
	v_mov_b32_e32 v50, v35
	s_waitcnt vmcnt(0)
	v_pk_mul_f32 v[50:51], v[50:51], v[134:135]
	v_mul_f32_e32 v34, v34, v132
	v_mul_f32_e32 v52, v64, v133
	v_mov_b32_e32 v35, v51
	v_mov_b32_e32 v53, v50
	v_pk_add_f32 v[34:35], v[34:35], v[52:53]

.LBB0_332:
	s_or_b64 exec, exec, s[6:7]
	s_waitcnt lgkmcnt(0)
	s_lshl_b64 s[4:5], s[14:15], 11
	v_ashrrev_i32_e32 v64, 5, v177
	v_lshl_add_u32 v67, v64, 4, v179
	ds_read2_b32 v[70:71], v67 offset1:1
	ds_read2_b32 v[72:73], v67 offset0:2 offset1:3
	ds_read2_b32 v[74:75], v67 offset0:8 offset1:9
	ds_read2_b32 v[76:77], v67 offset0:10 offset1:11
	ds_read2_b32 v[78:79], v67 offset0:16 offset1:17
	ds_read2_b32 v[80:81], v67 offset0:18 offset1:19
	ds_read2_b32 v[82:83], v67 offset0:24 offset1:25
	ds_read2_b32 v[84:85], v67 offset0:26 offset1:27
	s_add_u32 s4, s10, s4
	s_addc_u32 s5, s11, s5
	s_add_u32 s4, s4, s18
	s_addc_u32 s5, s5, s19
	s_add_i32 s31, s31, 1
	v_readlane_b32 s6, v254, 41
	v_readlane_b32 s7, v254, 42
	v_and_b32_e32 v65, 31, v177
	v_lshlrev_b32_e32 v66, 8, v178
	v_lshl_add_u32 v66, v64, 10, v66
	v_lshl_add_u32 v66, v65, 1, v66
	v_add_u32_e32 v66, 0x11000, v66
	s_waitcnt lgkmcnt(0)
	v_rcp_f32_e32 v70, v70
	v_rcp_f32_e32 v71, v71
	v_rcp_f32_e32 v72, v72
	v_rcp_f32_e32 v73, v73
	v_rcp_f32_e32 v74, v74
	v_rcp_f32_e32 v75, v75
	v_rcp_f32_e32 v76, v76
	v_rcp_f32_e32 v77, v77
	v_rcp_f32_e32 v78, v78
	v_rcp_f32_e32 v79, v79
	v_rcp_f32_e32 v80, v80
	v_rcp_f32_e32 v81, v81
	v_rcp_f32_e32 v82, v82
	v_rcp_f32_e32 v83, v83
	v_rcp_f32_e32 v84, v84
	v_rcp_f32_e32 v85, v85
	s_nop 1
	v_mul_f32_e32 v0, v0, v70
	v_cvt_pk_bf16_f32 v0, v0, v193
	ds_write_b16 v66, v0 offset:0
	v_mul_f32_e32 v48, v48, v70
	v_cvt_pk_bf16_f32 v48, v48, v193
	ds_write_b16 v66, v48 offset:64
	v_mul_f32_e32 v32, v32, v70
	v_cvt_pk_bf16_f32 v32, v32, v193
	ds_write_b16 v66, v32 offset:128
	v_mul_f32_e32 v16, v16, v70
	v_cvt_pk_bf16_f32 v16, v16, v193
	ds_write_b16 v66, v16 offset:192
	v_mul_f32_e32 v1, v1, v71
	v_cvt_pk_bf16_f32 v1, v1, v193
	ds_write_b16 v66, v1 offset:256
	v_mul_f32_e32 v49, v49, v71
	v_cvt_pk_bf16_f32 v49, v49, v193
	ds_write_b16 v66, v49 offset:320
	v_mul_f32_e32 v33, v33, v71
	v_cvt_pk_bf16_f32 v33, v33, v193
	ds_write_b16 v66, v33 offset:384
	v_mul_f32_e32 v17, v17, v71
	v_cvt_pk_bf16_f32 v17, v17, v193
	ds_write_b16 v66, v17 offset:448
	s_waitcnt lgkmcnt(7)
	v_mul_f32_e32 v2, v2, v72
	v_cvt_pk_bf16_f32 v2, v2, v193
	ds_write_b16 v66, v2 offset:512
	v_mul_f32_e32 v50, v50, v72
	v_cvt_pk_bf16_f32 v50, v50, v193
	ds_write_b16 v66, v50 offset:576
	v_mul_f32_e32 v34, v34, v72
	v_cvt_pk_bf16_f32 v34, v34, v193
	ds_write_b16 v66, v34 offset:640
	v_mul_f32_e32 v18, v18, v72
	v_cvt_pk_bf16_f32 v18, v18, v193
	ds_write_b16 v66, v18 offset:704
	v_mul_f32_e32 v3, v3, v73
	v_cvt_pk_bf16_f32 v3, v3, v193
	ds_write_b16 v66, v3 offset:768
	v_mul_f32_e32 v51, v51, v73
	v_cvt_pk_bf16_f32 v51, v51, v193
	ds_write_b16 v66, v51 offset:832
	v_mul_f32_e32 v35, v35, v73
	v_cvt_pk_bf16_f32 v35, v35, v193
	ds_write_b16 v66, v35 offset:896
	v_mul_f32_e32 v19, v19, v73
	v_cvt_pk_bf16_f32 v19, v19, v193
	ds_write_b16 v66, v19 offset:960
	s_waitcnt lgkmcnt(7)
	v_mul_f32_e32 v4, v4, v74
	v_cvt_pk_bf16_f32 v4, v4, v193
	ds_write_b16 v66, v4 offset:2048
	v_mul_f32_e32 v52, v52, v74
	v_cvt_pk_bf16_f32 v52, v52, v193
	ds_write_b16 v66, v52 offset:2112
	v_mul_f32_e32 v36, v36, v74
	v_cvt_pk_bf16_f32 v36, v36, v193
	ds_write_b16 v66, v36 offset:2176
	v_mul_f32_e32 v20, v20, v74
	v_cvt_pk_bf16_f32 v20, v20, v193
	ds_write_b16 v66, v20 offset:2240
	v_mul_f32_e32 v5, v5, v75
	v_cvt_pk_bf16_f32 v5, v5, v193
	ds_write_b16 v66, v5 offset:2304
	v_mul_f32_e32 v53, v53, v75
	v_cvt_pk_bf16_f32 v53, v53, v193
	ds_write_b16 v66, v53 offset:2368
	v_mul_f32_e32 v37, v37, v75
	v_cvt_pk_bf16_f32 v37, v37, v193
	ds_write_b16 v66, v37 offset:2432
	v_mul_f32_e32 v21, v21, v75
	v_cvt_pk_bf16_f32 v21, v21, v193
	ds_write_b16 v66, v21 offset:2496
	s_waitcnt lgkmcnt(7)
	v_mul_f32_e32 v6, v6, v76
	v_cvt_pk_bf16_f32 v6, v6, v193
	ds_write_b16 v66, v6 offset:2560
	v_mul_f32_e32 v54, v54, v76
	v_cvt_pk_bf16_f32 v54, v54, v193
	ds_write_b16 v66, v54 offset:2624
	v_mul_f32_e32 v38, v38, v76
	v_cvt_pk_bf16_f32 v38, v38, v193
	ds_write_b16 v66, v38 offset:2688
	v_mul_f32_e32 v22, v22, v76
	v_cvt_pk_bf16_f32 v22, v22, v193
	ds_write_b16 v66, v22 offset:2752
	v_mul_f32_e32 v7, v7, v77
	v_cvt_pk_bf16_f32 v7, v7, v193
	ds_write_b16 v66, v7 offset:2816
	v_mul_f32_e32 v55, v55, v77
	v_cvt_pk_bf16_f32 v55, v55, v193
	ds_write_b16 v66, v55 offset:2880
	v_mul_f32_e32 v39, v39, v77
	v_cvt_pk_bf16_f32 v39, v39, v193
	ds_write_b16 v66, v39 offset:2944
	v_mul_f32_e32 v23, v23, v77
	v_cvt_pk_bf16_f32 v23, v23, v193
	ds_write_b16 v66, v23 offset:3008
	s_waitcnt lgkmcnt(7)
	v_mul_f32_e32 v8, v8, v78
	v_cvt_pk_bf16_f32 v8, v8, v193
	ds_write_b16 v66, v8 offset:4096
	v_mul_f32_e32 v56, v56, v78
	v_cvt_pk_bf16_f32 v56, v56, v193
	ds_write_b16 v66, v56 offset:4160
	v_mul_f32_e32 v40, v40, v78
	v_cvt_pk_bf16_f32 v40, v40, v193
	ds_write_b16 v66, v40 offset:4224
	v_mul_f32_e32 v24, v24, v78
	v_cvt_pk_bf16_f32 v24, v24, v193
	ds_write_b16 v66, v24 offset:4288
	v_mul_f32_e32 v9, v9, v79
	v_cvt_pk_bf16_f32 v9, v9, v193
	ds_write_b16 v66, v9 offset:4352
	v_mul_f32_e32 v57, v57, v79
	v_cvt_pk_bf16_f32 v57, v57, v193
	ds_write_b16 v66, v57 offset:4416
	v_mul_f32_e32 v41, v41, v79
	v_cvt_pk_bf16_f32 v41, v41, v193
	ds_write_b16 v66, v41 offset:4480
	v_mul_f32_e32 v25, v25, v79
	v_cvt_pk_bf16_f32 v25, v25, v193
	ds_write_b16 v66, v25 offset:4544
	s_waitcnt lgkmcnt(7)
	v_mul_f32_e32 v10, v10, v80
	v_cvt_pk_bf16_f32 v10, v10, v193
	ds_write_b16 v66, v10 offset:4608
	v_mul_f32_e32 v58, v58, v80
	v_cvt_pk_bf16_f32 v58, v58, v193
	ds_write_b16 v66, v58 offset:4672
	v_mul_f32_e32 v42, v42, v80
	v_cvt_pk_bf16_f32 v42, v42, v193
	ds_write_b16 v66, v42 offset:4736
	v_mul_f32_e32 v26, v26, v80
	v_cvt_pk_bf16_f32 v26, v26, v193
	ds_write_b16 v66, v26 offset:4800
	v_mul_f32_e32 v11, v11, v81
	v_cvt_pk_bf16_f32 v11, v11, v193
	ds_write_b16 v66, v11 offset:4864
	v_mul_f32_e32 v59, v59, v81
	v_cvt_pk_bf16_f32 v59, v59, v193
	ds_write_b16 v66, v59 offset:4928
	v_mul_f32_e32 v43, v43, v81
	v_cvt_pk_bf16_f32 v43, v43, v193
	ds_write_b16 v66, v43 offset:4992
	v_mul_f32_e32 v27, v27, v81
	v_cvt_pk_bf16_f32 v27, v27, v193
	ds_write_b16 v66, v27 offset:5056
	s_waitcnt lgkmcnt(7)
	v_mul_f32_e32 v12, v12, v82
	v_cvt_pk_bf16_f32 v12, v12, v193
	ds_write_b16 v66, v12 offset:6144
	v_mul_f32_e32 v60, v60, v82
	v_cvt_pk_bf16_f32 v60, v60, v193
	ds_write_b16 v66, v60 offset:6208
	v_mul_f32_e32 v44, v44, v82
	v_cvt_pk_bf16_f32 v44, v44, v193
	ds_write_b16 v66, v44 offset:6272
	v_mul_f32_e32 v28, v28, v82
	v_cvt_pk_bf16_f32 v28, v28, v193
	ds_write_b16 v66, v28 offset:6336
	v_mul_f32_e32 v13, v13, v83
	v_cvt_pk_bf16_f32 v13, v13, v193
	ds_write_b16 v66, v13 offset:6400
	v_mul_f32_e32 v61, v61, v83
	v_cvt_pk_bf16_f32 v61, v61, v193
	ds_write_b16 v66, v61 offset:6464
	v_mul_f32_e32 v45, v45, v83
	v_cvt_pk_bf16_f32 v45, v45, v193
	ds_write_b16 v66, v45 offset:6528
	v_mul_f32_e32 v29, v29, v83
	v_cvt_pk_bf16_f32 v29, v29, v193
	ds_write_b16 v66, v29 offset:6592
	s_waitcnt lgkmcnt(7)
	v_mul_f32_e32 v14, v14, v84
	v_cvt_pk_bf16_f32 v14, v14, v193
	ds_write_b16 v66, v14 offset:6656
	v_mul_f32_e32 v62, v62, v84
	v_cvt_pk_bf16_f32 v62, v62, v193
	ds_write_b16 v66, v62 offset:6720
	v_mul_f32_e32 v46, v46, v84
	v_cvt_pk_bf16_f32 v46, v46, v193
	ds_write_b16 v66, v46 offset:6784
	v_mul_f32_e32 v30, v30, v84
	v_cvt_pk_bf16_f32 v30, v30, v193
	ds_write_b16 v66, v30 offset:6848
	v_mul_f32_e32 v15, v15, v85
	v_cvt_pk_bf16_f32 v15, v15, v193
	ds_write_b16 v66, v15 offset:6912
	v_mul_f32_e32 v63, v63, v85
	v_cvt_pk_bf16_f32 v63, v63, v193
	ds_write_b16 v66, v63 offset:6976
	v_mul_f32_e32 v47, v47, v85
	v_cvt_pk_bf16_f32 v47, v47, v193
	ds_write_b16 v66, v47 offset:7040
	v_mul_f32_e32 v31, v31, v85
	v_cvt_pk_bf16_f32 v31, v31, v193
	ds_write_b16 v66, v31 offset:7104
	v_lshrrev_b32_e32 v64, 4, v177
	v_and_b32_e32 v65, 15, v177
	v_lshlrev_b32_e32 v66, 8, v178
	v_lshl_add_u32 v66, v64, 8, v66
	v_lshl_add_u32 v66, v65, 4, v66
	v_add_u32_e32 v66, 0x11000, v66
	v_add_u32_e32 v68, v178, v64
	v_mov_b32_e32 v69, 0
	v_lshlrev_b64 v[68:69], 11, v[68:69]
	v_lshl_add_u64 v[68:69], s[4:5], 0, v[68:69]
	v_lshlrev_b32_e32 v70, 4, v65
	v_mov_b32_e32 v71, 0
	v_lshl_add_u64 v[68:69], v[68:69], 0, v[70:71]
	s_waitcnt lgkmcnt(0)
	ds_read_b128 v[0:3], v66 offset:0
	ds_read_b128 v[4:7], v66 offset:1024
	ds_read_b128 v[8:11], v66 offset:2048
	ds_read_b128 v[12:15], v66 offset:3072
	ds_read_b128 v[16:19], v66 offset:4096
	ds_read_b128 v[20:23], v66 offset:5120
	ds_read_b128 v[24:27], v66 offset:6144
	ds_read_b128 v[28:31], v66 offset:7168
	s_waitcnt lgkmcnt(7)
	global_store_dwordx4 v[68:69], v[0:3], off offset:1024
	v_add_co_u32_e32 v68, vcc, 0x2000, v68
	s_nop 1
	v_addc_co_u32_e32 v69, vcc, 0, v69, vcc
	s_waitcnt lgkmcnt(6)
	global_store_dwordx4 v[68:69], v[4:7], off offset:1024
	v_add_co_u32_e32 v68, vcc, 0x2000, v68
	s_nop 1
	v_addc_co_u32_e32 v69, vcc, 0, v69, vcc
	s_waitcnt lgkmcnt(5)
	global_store_dwordx4 v[68:69], v[8:11], off offset:1024
	v_add_co_u32_e32 v68, vcc, 0x2000, v68
	s_nop 1
	v_addc_co_u32_e32 v69, vcc, 0, v69, vcc
	s_waitcnt lgkmcnt(4)
	global_store_dwordx4 v[68:69], v[12:15], off offset:1024
	v_add_co_u32_e32 v68, vcc, 0x2000, v68
	s_nop 1
	v_addc_co_u32_e32 v69, vcc, 0, v69, vcc
	s_waitcnt lgkmcnt(3)
	global_store_dwordx4 v[68:69], v[16:19], off offset:1024
	v_add_co_u32_e32 v68, vcc, 0x2000, v68
	s_nop 1
	v_addc_co_u32_e32 v69, vcc, 0, v69, vcc
	s_waitcnt lgkmcnt(2)
	global_store_dwordx4 v[68:69], v[20:23], off offset:1024
	v_add_co_u32_e32 v68, vcc, 0x2000, v68
	s_nop 1
	v_addc_co_u32_e32 v69, vcc, 0, v69, vcc
	s_waitcnt lgkmcnt(1)
	global_store_dwordx4 v[68:69], v[24:27], off offset:1024
	v_add_co_u32_e32 v68, vcc, 0x2000, v68
	s_nop 1
	v_addc_co_u32_e32 v69, vcc, 0, v69, vcc
	s_waitcnt lgkmcnt(0)
	global_store_dwordx4 v[68:69], v[28:31], off offset:1024
	s_branch .Lattn_epi_pad_end
	s_nop 0
	s_nop 0
	s_nop 0
	s_nop 0
	s_nop 0
	s_nop 0
	s_nop 0
	s_nop 0
	s_nop 0
	s_nop 0
	s_nop 0
	s_nop 0
	s_nop 0
	s_nop 0
	s_nop 0
	s_nop 0
	s_nop 0
	s_nop 0
	s_nop 0
	s_nop 0
	s_nop 0
	s_nop 0
	s_nop 0
	s_nop 0
	s_nop 0
	s_nop 0
	s_nop 0
	s_nop 0
	s_nop 0
	s_nop 0
	s_nop 0
	s_nop 0
	s_nop 0
	s_nop 0
	s_nop 0
	s_nop 0
	s_nop 0
	s_nop 0
	s_nop 0
	s_nop 0
	s_nop 0
	s_nop 0
	s_nop 0
	s_nop 0
	s_nop 0
	s_nop 0
	s_nop 0
	s_nop 0
	s_nop 0
	s_nop 0
	s_nop 0
	s_nop 0
	s_nop 0
	s_nop 0
	s_nop 0
	s_nop 0
	s_nop 0
	s_nop 0
	s_nop 0
	s_nop 0
	s_nop 0
	s_nop 0
	s_nop 0
.Lattn_epi_pad_end:
	s_mul_i32 s4, s31, s82
	s_add_i32 s14, s4, s6
	s_cmpk_lt_i32 s14, 0x480
	s_cbranch_scc0 .LBB0_358
